# attention unit epilogue: 16 row-per-lane dwordx2 O stores paired into 8 dwordx4 via v_permlane32_swap (guide 7.3), on v42
# baseline (speedup 1.0000x reference)
; __device__ __forceinline__ unsigned cvt_pk_bf16(float lo, float hi) { f32x2 v = {lo, hi}; bf16x2_t b = __builtin_convertvector(v, bf16x2_t); return __builtin_bit_cast(unsigned, b); }
; #define ATT_BAR() do { asm volatile("s_waitcnt vmcnt(0) lgkmcnt(0)" ::: "memory"); __builtin_amdgcn_s_barrier(); asm volatile("" ::: "memory"); } while (0)
; __device__ __forceinline__ void att_mfma(const Params& P, LAS unsigned char* lds, int wave) {
;     ...
;         ATT_BAR();
;         const float lt = lrun + __shfl_xor(lrun, 32), il = 1.f / lt;
;         bf16_t* op = O + qrow_g * 1024 + hh * 128 + 4 * hf;
; #pragma unroll
;         for (int d = 0; d < 4; ++d)
; #pragma unroll
;             for (int j = 0; j < 4; ++j) { u32x2 w; w.x = cvt_pk_bf16(o[d][4 * j] * il, o[d][4 * j + 1] * il); w.y = cvt_pk_bf16(o[d][4 * j + 2] * il, o[d][4 * j + 3] * il);
;                 *(u32x2*)(op + d * 32 + 8 * j) = w; }
.LBB0_1007:
	v_and_b32_e32 v65, 64, v226
	v_xor_b32_e32 v64, 32, v226
	v_add_u32_e32 v65, 64, v65
	v_cmp_lt_i32_e32 vcc, v64, v65
	s_lshl_b32 s6, s47, 8
	s_waitcnt vmcnt(0) lgkmcnt(0)
	s_barrier
	v_cndmask_b32_e32 v64, v226, v64, vcc
	v_lshlrev_b32_e32 v64, 2, v64
	ds_bpermute_b32 v64, v64, v168
	s_add_i32 s39, s39, s56
	s_add_i32 s73, s73, s46
	s_add_i32 s38, s38, s56
	s_waitcnt lgkmcnt(0)
	v_add_f32_e32 v64, v168, v64
	v_div_scale_f32 v65, s[4:5], v64, v64, 1.0
	v_rcp_f32_e32 v66, v65
	s_cmpk_lt_i32 s39, 0x400
	v_fma_f32 v67, -v65, v66, 1.0
	v_fmac_f32_e32 v66, v67, v66
	v_div_scale_f32 v67, vcc, 1.0, v64, 1.0
	v_mul_f32_e32 v68, v67, v66
	v_fma_f32 v69, -v65, v68, v67
	v_fmac_f32_e32 v68, v69, v66
	v_fma_f32 v65, -v65, v68, v67
	v_div_fmas_f32 v65, v65, v66, v68
	v_lshlrev_b64 v[66:67], 11, v[164:165]
	v_div_fixup_f32 v64, v65, v64, 1.0
	v_lshl_add_u64 v[66:67], s[44:45], 0, v[66:67]
	v_lshl_add_u64 v[66:67], v[66:67], 0, s[6:7]
	v_lshl_add_u64 v[66:67], v[152:153], 1, v[66:67]
	v_and_b32_e32 v68, 32, v226
	v_mov_b32_e32 v69, 0
	v_lshrrev_b32_e32 v68, 2, v68
	v_lshl_add_u64 v[66:67], v[66:67], 0, v[68:69]
	v_pk_mul_f32 v[48:49], v[48:49], v[64:65] op_sel_hi:[1,0]
	v_pk_mul_f32 v[50:51], v[50:51], v[64:65] op_sel_hi:[1,0]
	v_pk_mul_f32 v[52:53], v[52:53], v[64:65] op_sel_hi:[1,0]
	v_pk_mul_f32 v[54:55], v[54:55], v[64:65] op_sel_hi:[1,0]
	v_cvt_pk_bf16_f32 v48, v48, v49
	v_cvt_pk_bf16_f32 v49, v50, v51
	v_cvt_pk_bf16_f32 v50, v52, v53
	v_cvt_pk_bf16_f32 v51, v54, v55
	s_nop 1
	v_permlane32_swap_b32_e32 v48, v50
	v_permlane32_swap_b32_e32 v49, v51
	v_pk_mul_f32 v[32:33], v[32:33], v[64:65] op_sel_hi:[1,0]
	v_pk_mul_f32 v[34:35], v[34:35], v[64:65] op_sel_hi:[1,0]
	v_pk_mul_f32 v[36:37], v[36:37], v[64:65] op_sel_hi:[1,0]
	v_pk_mul_f32 v[38:39], v[38:39], v[64:65] op_sel_hi:[1,0]
	v_cvt_pk_bf16_f32 v32, v32, v33
	v_cvt_pk_bf16_f32 v33, v34, v35
	v_cvt_pk_bf16_f32 v34, v36, v37
	v_cvt_pk_bf16_f32 v35, v38, v39
	s_nop 1
	v_permlane32_swap_b32_e32 v32, v34
	v_permlane32_swap_b32_e32 v33, v35
	global_store_dwordx4 v[66:67], v[48:51], off
	v_pk_mul_f32 v[16:17], v[16:17], v[64:65] op_sel_hi:[1,0]
	v_pk_mul_f32 v[18:19], v[18:19], v[64:65] op_sel_hi:[1,0]
	v_pk_mul_f32 v[20:21], v[20:21], v[64:65] op_sel_hi:[1,0]
	v_pk_mul_f32 v[22:23], v[22:23], v[64:65] op_sel_hi:[1,0]
	v_cvt_pk_bf16_f32 v16, v16, v17
	v_cvt_pk_bf16_f32 v17, v18, v19
	v_cvt_pk_bf16_f32 v18, v20, v21
	v_cvt_pk_bf16_f32 v19, v22, v23
	s_nop 1
	v_permlane32_swap_b32_e32 v16, v18
	v_permlane32_swap_b32_e32 v17, v19
	global_store_dwordx4 v[66:67], v[32:35], off offset:64
	v_pk_mul_f32 v[0:1], v[0:1], v[64:65] op_sel_hi:[1,0]
	v_pk_mul_f32 v[2:3], v[2:3], v[64:65] op_sel_hi:[1,0]
	v_pk_mul_f32 v[4:5], v[4:5], v[64:65] op_sel_hi:[1,0]
	v_pk_mul_f32 v[6:7], v[6:7], v[64:65] op_sel_hi:[1,0]
	v_cvt_pk_bf16_f32 v0, v0, v1
	v_cvt_pk_bf16_f32 v1, v2, v3
	v_cvt_pk_bf16_f32 v2, v4, v5
	v_cvt_pk_bf16_f32 v3, v6, v7
	s_nop 1
	v_permlane32_swap_b32_e32 v0, v2
	v_permlane32_swap_b32_e32 v1, v3
	global_store_dwordx4 v[66:67], v[16:19], off offset:128
	v_pk_mul_f32 v[56:57], v[56:57], v[64:65] op_sel_hi:[1,0]
	v_pk_mul_f32 v[58:59], v[58:59], v[64:65] op_sel_hi:[1,0]
	v_pk_mul_f32 v[60:61], v[60:61], v[64:65] op_sel_hi:[1,0]
	v_pk_mul_f32 v[62:63], v[62:63], v[64:65] op_sel_hi:[1,0]
	v_cvt_pk_bf16_f32 v56, v56, v57
	v_cvt_pk_bf16_f32 v57, v58, v59
	v_cvt_pk_bf16_f32 v58, v60, v61
	v_cvt_pk_bf16_f32 v59, v62, v63
	s_nop 1
	v_permlane32_swap_b32_e32 v56, v58
	v_permlane32_swap_b32_e32 v57, v59
	global_store_dwordx4 v[66:67], v[0:3], off offset:192
	v_pk_mul_f32 v[40:41], v[40:41], v[64:65] op_sel_hi:[1,0]
	v_pk_mul_f32 v[42:43], v[42:43], v[64:65] op_sel_hi:[1,0]
	v_pk_mul_f32 v[44:45], v[44:45], v[64:65] op_sel_hi:[1,0]
	v_pk_mul_f32 v[46:47], v[46:47], v[64:65] op_sel_hi:[1,0]
	v_cvt_pk_bf16_f32 v40, v40, v41
	v_cvt_pk_bf16_f32 v41, v42, v43
	v_cvt_pk_bf16_f32 v42, v44, v45
	v_cvt_pk_bf16_f32 v43, v46, v47
	s_nop 1
	v_permlane32_swap_b32_e32 v40, v42
	v_permlane32_swap_b32_e32 v41, v43
	global_store_dwordx4 v[66:67], v[56:59], off offset:32
	v_pk_mul_f32 v[24:25], v[24:25], v[64:65] op_sel_hi:[1,0]
	v_pk_mul_f32 v[26:27], v[26:27], v[64:65] op_sel_hi:[1,0]
	v_pk_mul_f32 v[28:29], v[28:29], v[64:65] op_sel_hi:[1,0]
	v_pk_mul_f32 v[30:31], v[30:31], v[64:65] op_sel_hi:[1,0]
	v_cvt_pk_bf16_f32 v24, v24, v25
	v_cvt_pk_bf16_f32 v25, v26, v27
	v_cvt_pk_bf16_f32 v26, v28, v29
	v_cvt_pk_bf16_f32 v27, v30, v31
	s_nop 1
	v_permlane32_swap_b32_e32 v24, v26
	v_permlane32_swap_b32_e32 v25, v27
	global_store_dwordx4 v[66:67], v[40:43], off offset:96
	v_pk_mul_f32 v[8:9], v[8:9], v[64:65] op_sel_hi:[1,0]
	v_pk_mul_f32 v[10:11], v[10:11], v[64:65] op_sel_hi:[1,0]
	v_pk_mul_f32 v[12:13], v[12:13], v[64:65] op_sel_hi:[1,0]
	v_pk_mul_f32 v[14:15], v[14:15], v[64:65] op_sel_hi:[1,0]
	v_cvt_pk_bf16_f32 v8, v8, v9
	v_cvt_pk_bf16_f32 v9, v10, v11
	v_cvt_pk_bf16_f32 v10, v12, v13
	v_cvt_pk_bf16_f32 v11, v14, v15
	s_nop 1
	v_permlane32_swap_b32_e32 v8, v10
	v_permlane32_swap_b32_e32 v9, v11
	global_store_dwordx4 v[66:67], v[24:27], off offset:160
	global_store_dwordx4 v[66:67], v[8:11], off offset:224
	s_cbranch_scc0 .LBB0_1028
